# MLA step after the stage barrier now leads with 28 softmax VALU ops before the first QK MFMA to cover the K-fragment LDS latency
# baseline (speedup 1.0000x reference)
; __device__ __forceinline__ float bf2f(unsigned short h) { return __uint_as_float((unsigned)h << 16); }
; template <bool MASK> __device__ __forceinline__ void sm_tile(f32x16& p0, f32x16& p1, float& mrun, float& lrun, f32x16& o0, f32x16& o1, LAS float* wsf, int kv0, int qpos, int q32, int hi) {
;     ...
;     float rs = 0.f;
; #pragma unroll
;     for (int r = 0; r < 16; ++r) { p0[r] = ex2(p0[r] - mrun); p1[r] = ex2(p1[r] - mrun); rs += p0[r] + p1[r]; }
;     rs += xhalf(rs, hi); lrun += rs;
; __device__ __forceinline__ void attn_unit_sm(int b, int h, int qb, const bf16_t* __restrict__ Q, const bf16_t* __restrict__ K, const bf16_t* __restrict__ K2, const bf16_t* __restrict__ Vt, bf16_t* __restrict__ O, const float* __restrict__ cs, LAS unsigned char* lds, int var) {
;     ...
;     SM_LOAD(0);
;     {
;         const float* cr = cs + (rowbase + q0 + wid * 32 + q32) * 32 + 8 * hi;
;         const f32x4 c0 = *(const f32x4*)cr, c1 = *(const f32x4*)(cr + 4), s0 = *(const f32x4*)(cr + 16), s1 = *(const f32x4*)(cr + 20);
;         const float cc[8] = {c0[0], c0[1], c0[2], c0[3], c1[0], c1[1], c1[2], c1[3]}, ss[8] = {s0[0], s0[1], s0[2], s0[3], s1[0], s1[1], s1[2], s1[3]};
;         float ra[8], rb[8];
; #pragma unroll
;         for (int i = 0; i < 8; ++i) { const float t1 = bf2f((unsigned short)qr[4][i]), t2 = bf2f((unsigned short)qr[5][i]); ra[i] = t1 * cc[i] - t2 * ss[i]; rb[i] = t1 * ss[i] + t2 * cc[i]; }
;         u32x4 wa, wb; wa.x = pk2(ra[0], ra[1]); wa.y = pk2(ra[2], ra[3]); wa.z = pk2(ra[4], ra[5]); wa.w = pk2(ra[6], ra[7]); wb.x = pk2(rb[0], rb[1]); wb.y = pk2(rb[2], rb[3]); wb.z = pk2(rb[4], rb[5]); wb.w = pk2(rb[6], rb[7]);
;         qr[4] = __builtin_bit_cast(bf16x8, wa); qr[5] = __builtin_bit_cast(bf16x8, wb); }
;     SM_STORE(0); __syncthreads();
;     SmState st;
; #pragma unroll
;     for (int r = 0; r < 16; ++r) { st.o0[r] = 0.f; st.o1[r] = 0.f; }
;     st.mrun = -INFINITY; st.lrun = 0.f;
;     int it = 0;
;     for (; it < ns - 2; ++it) {
;         const int cur = it & 1;
;         if (var != 2) SM_LOAD(it + 1);
; #pragma unroll
;         for (int sub = 0; sub < 2; ++sub)
;             sm_iter<false>(var, st, qr, lds + OFF_K + cur * KBUF + (sub * 64 + q32) * KP + hi * 16, lds + OFF_V + cur * VBUF + q32 * VP + sub * 128 + hi * 8, wsf, (2 * it + sub) * 64, qpos, q32, hi);
;         if (var != 2) SM_STORE(cur ^ 1);
;         __syncthreads();
.Lm3_ok4:
	s_xor_b32 s20, s43, 1
	s_mul_i32 s21, s20, 0x6800
	s_add_i32 s21, s21, 0
	s_mulk_i32 s20, 0x4200
	s_add_i32 s19, s19, 1
	v_lshl_add_u64 v[162:163], v[162:163], 0, s[94:95]
	v_lshl_add_u64 v[164:165], v[164:165], 0, s[96:97]
	v_lshl_add_u64 v[166:167], v[166:167], 0, s[38:39]
	s_cmp_eq_u32 s18, s19
	v_add_u32_e32 v1, s21, v150
	s_waitcnt vmcnt(4)
	ds_write_b128 v1, v[6:9]
	s_waitcnt vmcnt(3)
	ds_write_b128 v1, v[2:5] offset:13312
	v_add_u32_e32 v1, s21, v152
	s_waitcnt vmcnt(0)
	ds_write_b128 v1, v[112:115] offset:128
	v_add_u32_e32 v1, s20, v151
	v_add_u32_e32 v14, 0xd000, v1
	v_add_u32_e32 v1, 0xd080, v1
	ds_write2_b64 v14, v[10:11], v[12:13] offset1:1
	ds_write2_b64 v1, v[108:109], v[110:111] offset1:1
	s_waitcnt lgkmcnt(0)
	s_barrier
	s_cbranch_scc1 .Lm3_drain
	v_lshl_add_u64 v[2:3], s[22:23], 0, v[166:167]
	v_add_co_u32_e32 v4, vcc, 0x104a0000, v2
	v_lshl_add_u64 v[10:11], s[22:23], 0, v[162:163]
	s_nop 0
	v_addc_co_u32_e32 v5, vcc, 0, v3, vcc
	v_add_co_u32_e32 v2, vcc, 0x104c0000, v2
	s_and_b32 s43, s19, 1
	s_nop 0
	v_addc_co_u32_e32 v3, vcc, 0, v3, vcc
	v_add_co_u32_e32 v14, vcc, 0x12460000, v10
	global_load_dwordx4 v[6:9], v[4:5], off
	s_nop 0
	global_load_dwordx4 v[2:5], v[2:3], off
	v_addc_co_u32_e32 v15, vcc, 0, v11, vcc
	global_load_dwordx4 v[10:13], v[14:15], off offset:256
	global_load_dwordx4 v[108:111], v[14:15], off offset:384
	v_lshl_add_u64 v[14:15], s[22:23], 0, v[164:165]
	global_load_dwordx4 v[112:115], v[14:15], off
	s_mul_i32 s20, s43, 0x6800
	v_add_u32_e32 v1, s20, v175
	s_mul_i32 s20, s43, 0x4200
	v_add_u32_e32 v15, s20, v174
	v_add_u32_e32 v14, 0xd000, v15
	v_add_u32_e32 v176, 0xf000, v15
	ds_read_b128 v[116:119], v1 offset:0
	ds_read_b128 v[120:123], v1 offset:32
	ds_read_b128 v[124:127], v1 offset:64
	ds_read_b128 v[128:131], v1 offset:96
	ds_read_b128 v[132:135], v1 offset:128
	ds_read_b128 v[136:139], v1 offset:160
	v_exp_f32_e32 v48, v48
	v_exp_f32_e32 v49, v49
	v_exp_f32_e32 v50, v50
	v_add_f32_e32 v15, v48, v49
	v_exp_f32_e32 v51, v51
	v_cvt_pk_bf16_f32 v214, v48, v49
	v_exp_f32_e32 v52, v52
	v_add_f32_e32 v177, v50, v51
	v_exp_f32_e32 v53, v53
	v_cvt_pk_bf16_f32 v215, v50, v51
	v_exp_f32_e32 v54, v54
	v_add_f32_e32 v15, v15, v52
	v_exp_f32_e32 v55, v55
	v_add_f32_e32 v177, v177, v53
	v_exp_f32_e32 v56, v56
	v_cvt_pk_bf16_f32 v216, v52, v53
	v_exp_f32_e32 v57, v57
	v_add_f32_e32 v15, v15, v54
	v_exp_f32_e32 v58, v58
	v_add_f32_e32 v177, v177, v55
	v_exp_f32_e32 v59, v59
	v_cvt_pk_bf16_f32 v217, v54, v55
	v_exp_f32_e32 v60, v60
	v_add_f32_e32 v15, v15, v56
	v_exp_f32_e32 v61, v61
	v_add_f32_e32 v177, v177, v57
	v_exp_f32_e32 v62, v62
	v_cvt_pk_bf16_f32 v218, v56, v57
	s_waitcnt lgkmcnt(5)
	v_mfma_f32_32x32x16_bf16 v[64:79], v[116:119], v[84:87], v[198:213]
	v_exp_f32_e32 v63, v63
	v_add_f32_e32 v15, v15, v58
	s_waitcnt lgkmcnt(4)
	v_mfma_f32_32x32x16_bf16 v[64:79], v[120:123], v[88:91], v[64:79]
	v_add_f32_e32 v177, v177, v59
	v_cvt_pk_bf16_f32 v219, v58, v59
	s_waitcnt lgkmcnt(3)
	v_mfma_f32_32x32x16_bf16 v[64:79], v[124:127], v[92:95], v[64:79]
	v_add_f32_e32 v15, v15, v60
	v_add_f32_e32 v177, v177, v61
	s_waitcnt lgkmcnt(2)
	v_mfma_f32_32x32x16_bf16 v[64:79], v[128:131], v[96:99], v[64:79]
	v_cvt_pk_bf16_f32 v220, v60, v61
	v_add_f32_e32 v15, v15, v62
	s_waitcnt lgkmcnt(1)
	v_mfma_f32_32x32x16_bf16 v[64:79], v[132:135], v[100:103], v[64:79]
	v_add_f32_e32 v177, v177, v63
	v_cvt_pk_bf16_f32 v221, v62, v63
	s_waitcnt lgkmcnt(0)
	v_mfma_f32_32x32x16_bf16 v[64:79], v[136:139], v[104:107], v[64:79]
	v_add_f32_e32 v15, v15, v177
	v_add_f32_e32 v170, v170, v15
	s_waitcnt lgkmcnt(0)
	ds_read_b128 v[116:119], v1 offset:6656
	ds_read_b128 v[120:123], v1 offset:6688
	ds_read_b128 v[124:127], v1 offset:6720
	ds_read_b128 v[128:131], v1 offset:6752
	ds_read_b128 v[132:135], v1 offset:6784
	ds_read_b128 v[136:139], v1 offset:6816
	v_mfma_f32_32x32x16_bf16 v[16:31], v[214:217], v[140:143], v[16:31]
	ds_read2_b64 v[140:143], v14 offset0:0 offset1:2
	v_mfma_f32_32x32x16_bf16 v[32:47], v[214:217], v[144:147], v[32:47]
	ds_read2_b64 v[144:147], v176 offset0:32 offset1:34
	v_mfma_f32_32x32x16_bf16 v[16:31], v[218:221], v[180:183], v[16:31]
	ds_read2_b64 v[180:183], v14 offset0:4 offset1:6
	v_mfma_f32_32x32x16_bf16 v[32:47], v[218:221], v[184:187], v[32:47]
	ds_read2_b64 v[184:187], v176 offset0:36 offset1:38
	v_max3_f32 v15, v64, v65, v66
	v_max3_f32 v177, v67, v68, v69
	v_max3_f32 v15, v15, v70, v71
	v_max3_f32 v177, v177, v72, v73
	v_max3_f32 v15, v15, v74, v75
	v_max3_f32 v177, v177, v76, v77
	v_max3_f32 v15, v15, v78, v79
	v_max_f32_e32 v15, v15, v177
	v_mov_b32_e32 v177, v15
	v_mov_b32_e32 v178, v15
	s_nop 1
	v_permlane32_swap_b32_e32 v177, v178
	v_max3_f32 v15, v15, v177, v178
	v_cmp_gt_f32_e32 vcc, v15, v197
	s_cbranch_vccz .Lm3_ok5
	v_max_f32_e32 v15, v171, v15
	v_sub_f32_e32 v177, v171, v15
	v_exp_f32_e32 v177, v177
	v_sub_f32_e32 v198, v198, v15
	s_and_saveexec_b64 s[20:21], s[40:41]
	ds_write_b32 v149, v177
	s_or_b64 exec, exec, s[20:21]
	v_mul_f32_e32 v170, v170, v177
	v_add_u32_e32 v178, s25, v148
	s_waitcnt lgkmcnt(0)
	ds_read_b128 v[188:191], v178
	ds_read_b128 v[192:195], v178 offset:32
	ds_read_b128 v[222:225], v178 offset:64
	ds_read_b128 v[236:239], v178 offset:96
	v_sub_f32_e32 v64, v64, v15
	v_sub_f32_e32 v65, v65, v15
	v_sub_f32_e32 v66, v66, v15
	v_sub_f32_e32 v67, v67, v15
	v_sub_f32_e32 v68, v68, v15
	v_sub_f32_e32 v69, v69, v15
	v_sub_f32_e32 v70, v70, v15
	v_sub_f32_e32 v71, v71, v15
	v_sub_f32_e32 v72, v72, v15
	v_sub_f32_e32 v73, v73, v15
	v_sub_f32_e32 v74, v74, v15
	v_sub_f32_e32 v75, v75, v15
	v_sub_f32_e32 v76, v76, v15
	v_sub_f32_e32 v77, v77, v15
	v_sub_f32_e32 v78, v78, v15
	v_sub_f32_e32 v79, v79, v15
	v_mov_b32_e32 v199, v198
	v_mov_b32_e32 v200, v198
	v_mov_b32_e32 v201, v198
	v_mov_b32_e32 v202, v198
	v_mov_b32_e32 v203, v198
	v_mov_b32_e32 v204, v198
	v_mov_b32_e32 v205, v198
	v_mov_b32_e32 v206, v198
	v_mov_b32_e32 v207, v198
	v_mov_b32_e32 v208, v198
	v_mov_b32_e32 v209, v198
	v_mov_b32_e32 v210, v198
	v_mov_b32_e32 v211, v198
	v_mov_b32_e32 v212, v198
	v_mov_b32_e32 v213, v198
	v_mov_b32_e32 v171, 0
	v_mov_b32_e32 v197, 0x41000000
	s_nop 11
	s_nop 3
	s_waitcnt lgkmcnt(0)
	v_pk_mul_f32 v[16:17], v[16:17], v[188:189]
	v_pk_mul_f32 v[32:33], v[32:33], v[188:189]
	v_pk_mul_f32 v[18:19], v[18:19], v[190:191]
	v_pk_mul_f32 v[34:35], v[34:35], v[190:191]
	v_pk_mul_f32 v[20:21], v[20:21], v[192:193]
	v_pk_mul_f32 v[36:37], v[36:37], v[192:193]
	v_pk_mul_f32 v[22:23], v[22:23], v[194:195]
	v_pk_mul_f32 v[38:39], v[38:39], v[194:195]
	v_pk_mul_f32 v[24:25], v[24:25], v[222:223]
	v_pk_mul_f32 v[40:41], v[40:41], v[222:223]
	v_pk_mul_f32 v[26:27], v[26:27], v[224:225]
	v_pk_mul_f32 v[42:43], v[42:43], v[224:225]
	v_pk_mul_f32 v[28:29], v[28:29], v[236:237]
	v_pk_mul_f32 v[44:45], v[44:45], v[236:237]
	v_pk_mul_f32 v[30:31], v[30:31], v[238:239]
	v_pk_mul_f32 v[46:47], v[46:47], v[238:239]
